# both wave groups of the non-preparing workgroups decode for their first four pulls
# baseline (speedup 1.0000x reference)
; #define LAS __attribute__((address_space(3)))
; __device__ __forceinline__ void p3_scan_and_sb(const Params& P, float* lds) {
;     ...
;     } else {
;         const int grp = wave >> 2, gw = wave & 3;
;         volatile LAS unsigned* gctl = (volatile LAS unsigned*)((LAS unsigned char*)lds + LDS_CTL + 32);
;         if (tid < 8) gctl[tid] = 0u;
;         __syncthreads();
;         sba::Grp4 G; G.ctr = gctl + grp; G.gen = 0u;
;         if (grp == 1) sb_decode_wave_loop(P, lds);
.LBB0_939:
	s_cmp_lt_i32 s60, 4
	s_cselect_b64 s[0:1], -1, 0
	s_cmp_gt_i32 s61, 3
	s_cselect_b64 s[2:3], -1, 0
	s_and_b64 s[34:35], s[0:1], s[2:3]
	s_andn2_b64 vcc, exec, s[34:35]
	s_cbranch_vccnz .LBB0_1576
	v_writelane_b32 v252, s34, 54
	s_cmpk_lt_u32 s56, 0x60
	v_and_b32_e32 v1, 63, v0
	v_writelane_b32 v252, s35, 55
	v_writelane_b32 v252, s80, 56
	s_cselect_b64 s[52:53], -1, 0
	s_cmpk_gt_u32 s56, 0x5f
	v_writelane_b32 v252, s81, 57
	v_writelane_b32 v252, s56, 53
	v_writelane_b32 v252, s60, 51
	s_mov_b64 s[0:1], -1
	s_waitcnt vmcnt(0)
	v_writelane_b32 v252, s61, 52
	s_barrier
	v_writelane_b32 v252, s57, 50
	s_cbranch_scc0 .LBB0_1203
	v_writelane_b32 v252, s52, 58
	v_cmp_gt_u32_e32 vcc, 8, v0
	s_nop 0
	v_writelane_b32 v252, s53, 59
	s_and_saveexec_b64 s[0:1], vcc
	v_lshl_add_u32 v2, v0, 2, 0
	v_add_u32_e32 v2, 0x26020, v2
	v_mov_b32_e32 v3, 0
	ds_write_b32 v2, v3
	s_or_b64 exec, exec, s[0:1]
	v_lshrrev_b32_e32 v94, 8, v0
	s_waitcnt lgkmcnt(0)
	s_barrier
	v_cmp_eq_u32_e32 vcc, 1, v94
	s_mov_b64 s[0:1], exec
	v_writelane_b32 v252, s0, 60
	s_nop 1
	v_writelane_b32 v252, s1, 61
	s_cmpk_gt_u32 s56, 0xaa
	s_cselect_b64 s[2:3], exec, 0
	s_or_b64 vcc, vcc, s[2:3]
	s_and_b64 s[0:1], s[0:1], vcc
	s_mov_b64 exec, s[0:1]
	s_cbranch_execz .LBB0_1092
	v_readfirstlane_b32 s2, v94
	s_cmp_eq_u32 s2, 0
	s_cselect_b32 s100, 3, 0x7fffffff
	s_add_u32 s0, s78, 0x3900
	s_addc_u32 s1, s79, 0
	v_writelane_b32 v252, s0, 62
	v_mov_b32_e32 v95, 0
	v_cmp_eq_u32_e64 s[4:5], 0, v1
	v_writelane_b32 v252, s1, 63
	s_and_saveexec_b64 s[0:1], s[4:5]
	v_readlane_b32 s22, v252, 48
	v_readlane_b32 s23, v252, 49
	s_cbranch_execz .LBB0_948
	s_mov_b64 s[6:7], exec
	v_mbcnt_lo_u32_b32 v2, s6, 0
	v_mbcnt_hi_u32_b32 v2, s7, v2
	v_cmp_eq_u32_e32 vcc, 0, v2
	s_and_saveexec_b64 s[2:3], vcc
	s_cbranch_execz .LBB0_947
	s_bcnt1_i32_b64 s6, s[6:7]
	s_lshl_b32 s6, s6, 1
	v_mov_b32_e32 v4, s6
	v_readlane_b32 s6, v252, 62
	v_mov_b32_e32 v3, 0
	v_readlane_b32 s7, v252, 63
	s_nop 4
	global_atomic_add v3, v3, v4, s[6:7] sc0
